# nt (non-temporal) hint on the prep-phase x-row loads (read-once stream), otherwise identical to v108
# speedup vs baseline: 1.0170x; 1.0170x over previous
.LBB0_19:
	s_or_b64 exec, exec, s[14:15]
	v_lshlrev_b64 v[28:29], 13, v[28:29]
	v_lshl_add_u64 v[32:33], v[30:31], 0, v[28:29]
	v_lshl_add_u64 v[48:49], v[32:33], 0, v[2:3]
	global_load_dwordx4 v[28:31], v[48:49], off nt
	global_load_dwordx4 v[40:43], v[48:49], off offset:1024 nt
	v_mov_b32_e32 v17, v3
	v_mov_b32_e32 v19, v3
	global_load_dwordx4 v[44:47], v[48:49], off offset:2048 nt
	v_lshl_add_u64 v[52:53], v[32:33], 0, v[16:17]
	v_lshl_add_u64 v[56:57], v[32:33], 0, v[18:19]
	global_load_dwordx4 v[48:51], v[48:49], off offset:3072 nt
	s_nop 0
	global_load_dwordx4 v[52:55], v[52:53], off nt
	s_nop 0
	global_load_dwordx4 v[56:59], v[56:57], off nt
	v_mov_b32_e32 v21, v3
	v_mov_b32_e32 v23, v3
	v_lshl_add_u64 v[60:61], v[32:33], 0, v[20:21]
	v_lshl_add_u64 v[32:33], v[32:33], 0, v[22:23]
	global_load_dwordx4 v[60:63], v[60:61], off nt
	s_nop 0
	global_load_dwordx4 v[64:67], v[32:33], off nt
	v_cmp_lt_i32_e32 vcc, v36, v37
	s_waitcnt vmcnt(7)
	v_pk_mul_f32 v[72:73], v[28:29], v[28:29]
	s_waitcnt vmcnt(6)
	v_pk_mul_f32 v[76:77], v[40:41], v[40:41]
	v_pk_mul_f32 v[32:33], v[30:31], v[30:31]
	v_pk_mul_f32 v[74:75], v[42:43], v[42:43]
	s_waitcnt vmcnt(5)
	v_pk_mul_f32 v[80:81], v[44:45], v[44:45]
	v_add_f32_e32 v19, v76, v77
	v_add_f32_e32 v21, v72, v73
	v_pk_mul_f32 v[78:79], v[46:47], v[46:47]
	s_waitcnt vmcnt(4)
	v_pk_mul_f32 v[84:85], v[48:49], v[48:49]
	s_waitcnt vmcnt(3)
	v_mov_b32_e32 v92, v53
	s_waitcnt vmcnt(2)
	v_mov_b32_e32 v93, v57
	v_add_f32_e32 v23, v80, v81
	v_add_f32_e32 v19, v19, v74
	v_add_f32_e32 v21, v21, v32
	v_pk_mul_f32 v[82:83], v[50:51], v[50:51]
	v_mov_b32_e32 v90, v52
	v_mov_b32_e32 v91, v56
	v_pk_mul_f32 v[92:93], v[92:93], v[92:93]
	v_add_f32_e32 v25, v84, v85
	v_add_f32_e32 v23, v23, v78
	v_add_f32_e32 v19, v19, v75
	v_add_f32_e32 v21, v21, v33
	v_mov_b32_e32 v86, v54
	v_mov_b32_e32 v87, v58
	s_waitcnt vmcnt(1)
	v_mov_b32_e32 v100, v61
	s_waitcnt vmcnt(0)
	v_mov_b32_e32 v101, v65
	v_pk_fma_f32 v[72:73], v[90:91], v[90:91], v[92:93]
	v_add_f32_e32 v25, v25, v82
	v_add_f32_e32 v23, v23, v79
	v_add_f32_e32 v19, v21, v19
	v_mov_b32_e32 v88, v55
	v_mov_b32_e32 v89, v59
	v_mov_b32_e32 v98, v60
	v_mov_b32_e32 v99, v64
	v_pk_mul_f32 v[100:101], v[100:101], v[100:101]
	v_pk_fma_f32 v[72:73], v[86:87], v[86:87], v[72:73]
	v_add_f32_e32 v25, v25, v83
	v_add_f32_e32 v19, v19, v23
	v_mov_b32_e32 v94, v62
	v_mov_b32_e32 v95, v66
	v_pk_fma_f32 v[76:77], v[98:99], v[98:99], v[100:101]
	v_pk_fma_f32 v[32:33], v[88:89], v[88:89], v[72:73]
	v_add_f32_e32 v19, v19, v25
	v_mov_b32_e32 v96, v63
	v_mov_b32_e32 v97, v67
	v_pk_fma_f32 v[76:77], v[94:95], v[94:95], v[76:77]
	v_add_f32_e32 v19, v19, v32
	v_pk_fma_f32 v[72:73], v[96:97], v[96:97], v[76:77]
	v_add_f32_e32 v19, v19, v33
	v_add_f32_e32 v19, v19, v72
	v_add_f32_e32 v19, v19, v73
	v_cndmask_b32_e32 v17, v35, v36, vcc
	v_lshlrev_b32_e32 v17, 2, v17
	v_add_f32_dpp v19, v19, v19 quad_perm:[1,0,3,2] row_mask:0xf bank_mask:0xf bound_ctrl:1
	v_cmp_lt_i32_e32 vcc, v38, v37
	v_mov_b32_e32 v25, v3
	v_add_f32_dpp v19, v19, v19 quad_perm:[2,3,0,1] row_mask:0xf bank_mask:0xf bound_ctrl:1
	v_cndmask_b32_e32 v21, v35, v38, vcc
	v_lshlrev_b32_e32 v21, 2, v21
	v_add_f32_dpp v19, v19, v19 row_half_mirror row_mask:0xf bank_mask:0xf bound_ctrl:1
	v_lshl_add_u64 v[32:33], v[26:27], 0, v[24:25]
	s_nop 0
	v_add_f32_dpp v19, v19, v19 row_mirror row_mask:0xf bank_mask:0xf bound_ctrl:1
	ds_bpermute_b32 v17, v17, v19
	s_waitcnt lgkmcnt(0)
	v_add_f32_e32 v17, v19, v17
	ds_bpermute_b32 v19, v21, v17
	s_waitcnt lgkmcnt(0)
	v_add_f32_e32 v17, v17, v19
	v_fmamk_f32 v17, v17, 0x3a000000, v34
	v_mul_f32_e32 v19, 0x4b800000, v17
	v_cmp_gt_f32_e32 vcc, s23, v17
	s_nop 1
	v_cndmask_b32_e32 v17, v17, v19, vcc
	v_rsq_f32_e32 v17, v17
	s_nop 0
	v_mul_f32_e32 v19, 0x45800000, v17
	v_cndmask_b32_e32 v72, v17, v19, vcc
	v_pk_mul_f32 v[26:27], v[28:29], v[72:73] op_sel_hi:[1,0]
	v_pk_mul_f32 v[28:29], v[30:31], v[72:73] op_sel_hi:[1,0]
	v_pk_mul_f32 v[26:27], v[182:183], v[26:27]
	v_pk_mul_f32 v[28:29], v[184:185], v[28:29]
	v_cvt_pk_bf16_f32 v26, v26, v27
	v_cvt_pk_bf16_f32 v27, v28, v29
	global_store_dwordx2 v[32:33], v[26:27], off
	v_pk_mul_f32 v[30:31], v[40:41], v[72:73] op_sel_hi:[1,0]
	v_pk_mul_f32 v[40:41], v[42:43], v[72:73] op_sel_hi:[1,0]
	v_pk_mul_f32 v[26:27], v[186:187], v[30:31]
	v_pk_mul_f32 v[28:29], v[188:189], v[40:41]
	v_cvt_pk_bf16_f32 v26, v26, v27
	v_cvt_pk_bf16_f32 v27, v28, v29
	global_store_dwordx2 v[32:33], v[26:27], off offset:512
	v_pk_mul_f32 v[30:31], v[44:45], v[72:73] op_sel_hi:[1,0]
	v_pk_mul_f32 v[40:41], v[46:47], v[72:73] op_sel_hi:[1,0]
	v_pk_mul_f32 v[26:27], v[30:31], v[190:191]
	v_pk_mul_f32 v[28:29], v[40:41], v[192:193]
	v_cvt_pk_bf16_f32 v26, v26, v27
	v_cvt_pk_bf16_f32 v27, v28, v29
	global_store_dwordx2 v[32:33], v[26:27], off offset:1024
	v_pk_mul_f32 v[30:31], v[48:49], v[72:73] op_sel_hi:[1,0]
	v_pk_mul_f32 v[40:41], v[50:51], v[72:73] op_sel_hi:[1,0]
	v_pk_mul_f32 v[26:27], v[30:31], v[194:195]
	v_pk_mul_f32 v[28:29], v[40:41], v[196:197]
	v_cvt_pk_bf16_f32 v26, v26, v27
	v_cvt_pk_bf16_f32 v27, v28, v29
	global_store_dwordx2 v[32:33], v[26:27], off offset:1536
	v_pk_mul_f32 v[30:31], v[52:53], v[72:73] op_sel_hi:[1,0]
	v_pk_mul_f32 v[40:41], v[54:55], v[72:73] op_sel_hi:[1,0]
	v_pk_mul_f32 v[26:27], v[30:31], v[198:199]
	v_pk_mul_f32 v[28:29], v[40:41], v[200:201]
	v_cvt_pk_bf16_f32 v26, v26, v27
	v_cvt_pk_bf16_f32 v27, v28, v29
	global_store_dwordx2 v[32:33], v[26:27], off offset:2048
	v_pk_mul_f32 v[30:31], v[56:57], v[72:73] op_sel_hi:[1,0]
	v_pk_mul_f32 v[40:41], v[58:59], v[72:73] op_sel_hi:[1,0]
	v_pk_mul_f32 v[26:27], v[30:31], v[202:203]
	v_pk_mul_f32 v[28:29], v[40:41], v[204:205]
	v_cvt_pk_bf16_f32 v26, v26, v27
	v_cvt_pk_bf16_f32 v27, v28, v29
	global_store_dwordx2 v[32:33], v[26:27], off offset:2560
	v_pk_mul_f32 v[30:31], v[60:61], v[72:73] op_sel_hi:[1,0]
	v_pk_mul_f32 v[40:41], v[62:63], v[72:73] op_sel_hi:[1,0]
	v_pk_mul_f32 v[26:27], v[30:31], v[206:207]
	v_pk_mul_f32 v[28:29], v[40:41], v[208:209]
	v_cvt_pk_bf16_f32 v26, v26, v27
	v_cvt_pk_bf16_f32 v27, v28, v29
	global_store_dwordx2 v[32:33], v[26:27], off offset:3072
	v_pk_mul_f32 v[30:31], v[64:65], v[72:73] op_sel_hi:[1,0]
	v_pk_mul_f32 v[40:41], v[66:67], v[72:73] op_sel_hi:[1,0]
	v_pk_mul_f32 v[26:27], v[30:31], v[210:211]
	v_pk_mul_f32 v[28:29], v[40:41], v[212:213]
	v_cvt_pk_bf16_f32 v26, v26, v27
	v_cvt_pk_bf16_f32 v27, v28, v29
	global_store_dwordx2 v[32:33], v[26:27], off offset:3584
